# attention finalize: the 16 sub-layer-norm weight loads issued 8 ahead into idle fragment registers, counted vmcnt instead of vmcnt(0) per row group
# baseline (speedup 1.0000x reference)
.LBB0_737:
	s_andn2_b64 vcc, exec, s[82:83]
	s_waitcnt lgkmcnt(0)
	s_barrier
	s_cbranch_vccnz .LBB0_686
	ds_read2st64_b32 v[100:101], v3 offset1:1
	s_waitcnt lgkmcnt(0)
	v_pk_fma_f32 v[100:101], v[160:161], v[116:117], v[100:101] op_sel_hi:[1,0,1] neg_lo:[0,0,1] neg_hi:[0,0,1]
	s_nop 0
	v_mul_f32_e32 v102, v101, v101
	v_pk_fma_f32 v[104:105], v[100:101], v[100:101], v[102:103] op_sel_hi:[1,1,0]
	ds_read2st64_b32 v[102:103], v3 offset0:2 offset1:3
	s_waitcnt lgkmcnt(0)
	v_pk_fma_f32 v[102:103], v[162:163], v[116:117], v[102:103] op_sel_hi:[1,0,1] neg_lo:[0,0,1] neg_hi:[0,0,1]
	s_nop 0
	v_pk_fma_f32 v[104:105], v[102:103], v[102:103], v[104:105]
	v_mul_f32_e32 v106, v103, v103
	v_pk_add_f32 v[110:111], v[104:105], v[106:107] op_sel_hi:[1,0]
	ds_read2st64_b32 v[104:105], v3 offset0:4 offset1:5
	s_waitcnt lgkmcnt(0)
	v_pk_fma_f32 v[104:105], v[156:157], v[2:3], v[104:105] op_sel_hi:[1,0,1] neg_lo:[0,0,1] neg_hi:[0,0,1]
	s_nop 0
	v_mul_f32_e32 v106, v105, v105
	v_pk_fma_f32 v[108:109], v[104:105], v[104:105], v[106:107] op_sel_hi:[1,1,0]
	ds_read2st64_b32 v[106:107], v3 offset0:6 offset1:7
	s_waitcnt lgkmcnt(0)
	v_pk_fma_f32 v[106:107], v[158:159], v[2:3], v[106:107] op_sel_hi:[1,0,1] neg_lo:[0,0,1] neg_hi:[0,0,1]
	s_nop 0
	v_pk_fma_f32 v[108:109], v[106:107], v[106:107], v[108:109]
	v_mul_f32_e32 v112, v107, v107
	v_pk_add_f32 v[112:113], v[108:109], v[112:113] op_sel_hi:[1,0]
	ds_read2st64_b32 v[118:119], v3 offset0:14 offset1:15
	ds_read2st64_b32 v[120:121], v3 offset0:12 offset1:13
	ds_read2st64_b32 v[114:115], v3 offset0:10 offset1:11
	ds_read2st64_b32 v[108:109], v3 offset0:8 offset1:9
	s_waitcnt lgkmcnt(1)
	v_pk_fma_f32 v[114:115], v[154:155], v[116:117], v[114:115] op_sel_hi:[1,0,1] neg_lo:[0,0,1] neg_hi:[0,0,1]
	s_waitcnt lgkmcnt(0)
	v_pk_fma_f32 v[108:109], v[152:153], v[116:117], v[108:109] op_sel_hi:[1,0,1] neg_lo:[0,0,1] neg_hi:[0,0,1]
	s_nop 0
	v_pk_fma_f32 v[110:111], v[108:109], v[108:109], v[110:111]
	v_mul_f32_e32 v122, v109, v109
	v_pk_add_f32 v[110:111], v[122:123], v[110:111] op_sel_hi:[0,1]
	v_pk_fma_f32 v[110:111], v[114:115], v[114:115], v[110:111]
	v_mul_f32_e32 v122, v115, v115
	v_pk_add_f32 v[122:123], v[122:123], v[110:111] op_sel_hi:[0,1]
	v_pk_fma_f32 v[110:111], v[148:149], v[2:3], v[120:121] op_sel_hi:[1,0,1] neg_lo:[0,0,1] neg_hi:[0,0,1]
	s_nop 0
	v_pk_fma_f32 v[112:113], v[110:111], v[110:111], v[112:113]
	v_mul_f32_e32 v120, v111, v111
	v_pk_add_f32 v[120:121], v[120:121], v[112:113] op_sel_hi:[0,1]
	v_pk_fma_f32 v[112:113], v[150:151], v[2:3], v[118:119] op_sel_hi:[1,0,1] neg_lo:[0,0,1] neg_hi:[0,0,1]
	s_nop 0
	v_pk_fma_f32 v[118:119], v[112:113], v[112:113], v[120:121]
	v_mul_f32_e32 v120, v113, v113
	v_pk_add_f32 v[126:127], v[120:121], v[118:119] op_sel_hi:[0,1]
	ds_read2st64_b32 v[128:129], v3 offset0:22 offset1:23
	ds_read2st64_b32 v[120:121], v3 offset0:20 offset1:21
	ds_read2st64_b32 v[124:125], v3 offset0:18 offset1:19
	ds_read2st64_b32 v[118:119], v3 offset0:16 offset1:17
	s_waitcnt lgkmcnt(2)
	v_pk_fma_f32 v[120:121], v[140:141], v[2:3], v[120:121] op_sel_hi:[1,0,1] neg_lo:[0,0,1] neg_hi:[0,0,1]
	s_waitcnt lgkmcnt(1)
	v_pk_fma_f32 v[124:125], v[146:147], v[116:117], v[124:125] op_sel_hi:[1,0,1] neg_lo:[0,0,1] neg_hi:[0,0,1]
	s_waitcnt lgkmcnt(0)
	v_pk_fma_f32 v[118:119], v[144:145], v[116:117], v[118:119] op_sel_hi:[1,0,1] neg_lo:[0,0,1] neg_hi:[0,0,1]
	s_nop 0
	v_pk_fma_f32 v[122:123], v[118:119], v[118:119], v[122:123]
	v_mul_f32_e32 v130, v119, v119
	v_pk_add_f32 v[122:123], v[130:131], v[122:123] op_sel_hi:[0,1]
	v_pk_fma_f32 v[122:123], v[124:125], v[124:125], v[122:123]
	v_mul_f32_e32 v130, v125, v125
	v_pk_add_f32 v[130:131], v[130:131], v[122:123] op_sel_hi:[0,1]
	v_pk_fma_f32 v[122:123], v[120:121], v[120:121], v[126:127]
	v_mul_f32_e32 v126, v121, v121
	v_pk_add_f32 v[126:127], v[126:127], v[122:123] op_sel_hi:[0,1]
	v_pk_fma_f32 v[122:123], v[142:143], v[2:3], v[128:129] op_sel_hi:[1,0,1] neg_lo:[0,0,1] neg_hi:[0,0,1]
	s_nop 0
	v_pk_fma_f32 v[126:127], v[122:123], v[122:123], v[126:127]
	v_mul_f32_e32 v128, v123, v123
	v_pk_add_f32 v[140:141], v[128:129], v[126:127] op_sel_hi:[0,1]
	ds_read2st64_b32 v[142:143], v3 offset0:30 offset1:31
	ds_read2st64_b32 v[128:129], v3 offset0:28 offset1:29
	ds_read2st64_b32 v[144:145], v3 offset0:26 offset1:27
	ds_read2st64_b32 v[126:127], v3 offset0:24 offset1:25
	s_waitcnt lgkmcnt(2)
	v_pk_fma_f32 v[128:129], v[132:133], v[2:3], v[128:129] op_sel_hi:[1,0,1] neg_lo:[0,0,1] neg_hi:[0,0,1]
	s_nop 0
	v_pk_fma_f32 v[132:133], v[128:129], v[128:129], v[140:141]
	s_waitcnt lgkmcnt(0)
	v_pk_fma_f32 v[126:127], v[136:137], v[116:117], v[126:127] op_sel_hi:[1,0,1] neg_lo:[0,0,1] neg_hi:[0,0,1]
	s_nop 0
	v_pk_fma_f32 v[130:131], v[126:127], v[126:127], v[130:131]
	v_mul_f32_e32 v136, v127, v127
	v_pk_add_f32 v[136:137], v[136:137], v[130:131] op_sel_hi:[0,1]
	v_pk_fma_f32 v[130:131], v[138:139], v[116:117], v[144:145] op_sel_hi:[1,0,1] neg_lo:[0,0,1] neg_hi:[0,0,1]
	s_nop 0
	v_pk_fma_f32 v[136:137], v[130:131], v[130:131], v[136:137]
	v_mul_f32_e32 v138, v131, v131
	v_pk_add_f32 v[136:137], v[138:139], v[136:137] op_sel_hi:[0,1]
	v_mul_f32_e32 v138, v129, v129
	v_pk_add_f32 v[138:139], v[138:139], v[132:133] op_sel_hi:[0,1]
	v_pk_fma_f32 v[132:133], v[134:135], v[2:3], v[142:143] op_sel_hi:[1,0,1] neg_lo:[0,0,1] neg_hi:[0,0,1]
	s_nop 0
	v_pk_fma_f32 v[134:135], v[132:133], v[132:133], v[138:139]
	v_mul_f32_e32 v138, v133, v133
	v_pk_add_f32 v[134:135], v[138:139], v[134:135] op_sel_hi:[0,1]
	ds_read2st64_b32 v[138:139], v3 offset0:32 offset1:33
	s_waitcnt lgkmcnt(0)
	v_pk_fma_f32 v[96:97], v[96:97], v[116:117], v[138:139] op_sel_hi:[1,0,1] neg_lo:[0,0,1] neg_hi:[0,0,1]
	s_nop 0
	v_pk_fma_f32 v[136:137], v[96:97], v[96:97], v[136:137]
	v_mul_f32_e32 v138, v97, v97
	v_pk_add_f32 v[136:137], v[138:139], v[136:137] op_sel_hi:[0,1]
	ds_read2st64_b32 v[138:139], v3 offset0:34 offset1:35
	s_waitcnt lgkmcnt(0)
	v_pk_fma_f32 v[98:99], v[98:99], v[116:117], v[138:139] op_sel_hi:[1,0,1] neg_lo:[0,0,1] neg_hi:[0,0,1]
	s_nop 0
	v_pk_fma_f32 v[136:137], v[98:99], v[98:99], v[136:137]
	v_mul_f32_e32 v138, v99, v99
	v_pk_add_f32 v[136:137], v[138:139], v[136:137] op_sel_hi:[0,1]
	ds_read2st64_b32 v[138:139], v3 offset0:36 offset1:37
	s_waitcnt lgkmcnt(0)
	v_pk_fma_f32 v[92:93], v[92:93], v[2:3], v[138:139] op_sel_hi:[1,0,1] neg_lo:[0,0,1] neg_hi:[0,0,1]
	s_nop 0
	v_pk_fma_f32 v[134:135], v[92:93], v[92:93], v[134:135]
	v_mul_f32_e32 v138, v93, v93
	v_pk_add_f32 v[134:135], v[134:135], v[138:139] op_sel_hi:[1,0]
	ds_read2st64_b32 v[138:139], v3 offset0:38 offset1:39
	s_waitcnt lgkmcnt(0)
	v_pk_fma_f32 v[94:95], v[94:95], v[2:3], v[138:139] op_sel_hi:[1,0,1] neg_lo:[0,0,1] neg_hi:[0,0,1]
	s_nop 0
	v_pk_fma_f32 v[134:135], v[94:95], v[94:95], v[134:135]
	v_mul_f32_e32 v138, v95, v95
	v_pk_add_f32 v[134:135], v[134:135], v[138:139] op_sel_hi:[1,0]
	ds_read2st64_b32 v[138:139], v3 offset0:46 offset1:47
	ds_read2st64_b32 v[140:141], v3 offset0:44 offset1:45
	ds_read2st64_b32 v[142:143], v3 offset0:42 offset1:43
	ds_read2st64_b32 v[144:145], v3 offset0:40 offset1:41
	s_waitcnt lgkmcnt(3)
	v_pk_fma_f32 v[86:87], v[86:87], v[2:3], v[138:139] op_sel_hi:[1,0,1] neg_lo:[0,0,1] neg_hi:[0,0,1]
	s_waitcnt lgkmcnt(2)
	v_pk_fma_f32 v[84:85], v[84:85], v[2:3], v[140:141] op_sel_hi:[1,0,1] neg_lo:[0,0,1] neg_hi:[0,0,1]
	s_waitcnt lgkmcnt(1)
	v_pk_fma_f32 v[90:91], v[90:91], v[116:117], v[142:143] op_sel_hi:[1,0,1] neg_lo:[0,0,1] neg_hi:[0,0,1]
	s_waitcnt lgkmcnt(0)
	v_pk_fma_f32 v[88:89], v[88:89], v[116:117], v[144:145] op_sel_hi:[1,0,1] neg_lo:[0,0,1] neg_hi:[0,0,1]
	v_pk_fma_f32 v[134:135], v[84:85], v[84:85], v[134:135]
	v_pk_fma_f32 v[136:137], v[88:89], v[88:89], v[136:137]
	v_mul_f32_e32 v144, v89, v89
	v_mul_f32_e32 v140, v85, v85
	v_pk_add_f32 v[136:137], v[144:145], v[136:137] op_sel_hi:[0,1]
	v_pk_add_f32 v[134:135], v[140:141], v[134:135] op_sel_hi:[0,1]
	v_pk_fma_f32 v[136:137], v[90:91], v[90:91], v[136:137]
	v_mul_f32_e32 v142, v91, v91
	v_pk_fma_f32 v[134:135], v[86:87], v[86:87], v[134:135]
	v_mul_f32_e32 v138, v87, v87
	v_pk_add_f32 v[136:137], v[142:143], v[136:137] op_sel_hi:[0,1]
	v_pk_add_f32 v[134:135], v[138:139], v[134:135] op_sel_hi:[0,1]
	ds_read2st64_b32 v[138:139], v3 offset0:54 offset1:55
	ds_read2st64_b32 v[140:141], v3 offset0:52 offset1:53
	ds_read2st64_b32 v[142:143], v3 offset0:50 offset1:51
	ds_read2st64_b32 v[144:145], v3 offset0:48 offset1:49
	s_waitcnt lgkmcnt(3)
	v_pk_fma_f32 v[78:79], v[78:79], v[2:3], v[138:139] op_sel_hi:[1,0,1] neg_lo:[0,0,1] neg_hi:[0,0,1]
	s_waitcnt lgkmcnt(2)
	v_pk_fma_f32 v[76:77], v[76:77], v[2:3], v[140:141] op_sel_hi:[1,0,1] neg_lo:[0,0,1] neg_hi:[0,0,1]
	s_waitcnt lgkmcnt(1)
	v_pk_fma_f32 v[82:83], v[82:83], v[116:117], v[142:143] op_sel_hi:[1,0,1] neg_lo:[0,0,1] neg_hi:[0,0,1]
	s_waitcnt lgkmcnt(0)
	v_pk_fma_f32 v[80:81], v[80:81], v[116:117], v[144:145] op_sel_hi:[1,0,1] neg_lo:[0,0,1] neg_hi:[0,0,1]
	v_pk_fma_f32 v[134:135], v[76:77], v[76:77], v[134:135]
	v_pk_fma_f32 v[136:137], v[80:81], v[80:81], v[136:137]
	v_mul_f32_e32 v144, v81, v81
	v_mul_f32_e32 v140, v77, v77
	v_pk_add_f32 v[136:137], v[144:145], v[136:137] op_sel_hi:[0,1]
	v_pk_add_f32 v[134:135], v[140:141], v[134:135] op_sel_hi:[0,1]
	v_pk_fma_f32 v[136:137], v[82:83], v[82:83], v[136:137]
	v_mul_f32_e32 v142, v83, v83
	v_pk_fma_f32 v[134:135], v[78:79], v[78:79], v[134:135]
	v_mul_f32_e32 v138, v79, v79
	v_pk_add_f32 v[136:137], v[142:143], v[136:137] op_sel_hi:[0,1]
	v_pk_add_f32 v[134:135], v[138:139], v[134:135] op_sel_hi:[0,1]
	ds_read2st64_b32 v[138:139], v3 offset0:62 offset1:63
	ds_read2st64_b32 v[140:141], v3 offset0:60 offset1:61
	ds_read2st64_b32 v[142:143], v3 offset0:58 offset1:59
	ds_read2st64_b32 v[144:145], v3 offset0:56 offset1:57
	s_waitcnt lgkmcnt(3)
	v_pk_fma_f32 v[70:71], v[70:71], v[2:3], v[138:139] op_sel_hi:[1,0,1] neg_lo:[0,0,1] neg_hi:[0,0,1]
	s_waitcnt lgkmcnt(2)
	v_pk_fma_f32 v[68:69], v[68:69], v[2:3], v[140:141] op_sel_hi:[1,0,1] neg_lo:[0,0,1] neg_hi:[0,0,1]
	v_mul_f32_e32 v138, v71, v71
	v_pk_fma_f32 v[134:135], v[68:69], v[68:69], v[134:135]
	v_mul_f32_e32 v140, v69, v69
	v_pk_add_f32 v[134:135], v[140:141], v[134:135] op_sel_hi:[0,1]
	v_pk_fma_f32 v[134:135], v[70:71], v[70:71], v[134:135]
	s_waitcnt lgkmcnt(0)
	v_pk_fma_f32 v[72:73], v[72:73], v[116:117], v[144:145] op_sel_hi:[1,0,1] neg_lo:[0,0,1] neg_hi:[0,0,1]
	v_pk_add_f32 v[134:135], v[138:139], v[134:135] op_sel_hi:[0,1]
	ds_read2st64_b32 v[138:139], v3 offset0:64 offset1:65
	v_pk_fma_f32 v[136:137], v[72:73], v[72:73], v[136:137]
	v_mul_f32_e32 v144, v73, v73
	v_pk_add_f32 v[136:137], v[144:145], v[136:137] op_sel_hi:[0,1]
	v_pk_fma_f32 v[74:75], v[74:75], v[116:117], v[142:143] op_sel_hi:[1,0,1] neg_lo:[0,0,1] neg_hi:[0,0,1]
	s_waitcnt lgkmcnt(0)
	v_pk_fma_f32 v[64:65], v[64:65], v[116:117], v[138:139] op_sel_hi:[1,0,1] neg_lo:[0,0,1] neg_hi:[0,0,1]
	v_pk_fma_f32 v[136:137], v[74:75], v[74:75], v[136:137]
	v_mul_f32_e32 v142, v75, v75
	v_pk_add_f32 v[136:137], v[142:143], v[136:137] op_sel_hi:[0,1]
	v_pk_fma_f32 v[136:137], v[64:65], v[64:65], v[136:137]
	v_mul_f32_e32 v138, v65, v65
	v_pk_add_f32 v[136:137], v[138:139], v[136:137] op_sel_hi:[0,1]
	ds_read2st64_b32 v[138:139], v3 offset0:66 offset1:67
	s_waitcnt lgkmcnt(0)
	v_pk_fma_f32 v[66:67], v[66:67], v[116:117], v[138:139] op_sel_hi:[1,0,1] neg_lo:[0,0,1] neg_hi:[0,0,1]
	s_nop 0
	v_pk_fma_f32 v[136:137], v[66:67], v[66:67], v[136:137]
	v_mul_f32_e32 v138, v67, v67
	v_pk_add_f32 v[136:137], v[138:139], v[136:137] op_sel_hi:[0,1]
	ds_read2st64_b32 v[138:139], v3 offset0:68 offset1:69
	s_waitcnt lgkmcnt(0)
	v_pk_fma_f32 v[60:61], v[60:61], v[2:3], v[138:139] op_sel_hi:[1,0,1] neg_lo:[0,0,1] neg_hi:[0,0,1]
	s_nop 0
	v_pk_fma_f32 v[134:135], v[60:61], v[60:61], v[134:135]
	v_mul_f32_e32 v138, v61, v61
	v_pk_add_f32 v[134:135], v[134:135], v[138:139] op_sel_hi:[1,0]
	ds_read2st64_b32 v[138:139], v3 offset0:70 offset1:71
	s_waitcnt lgkmcnt(0)
	v_pk_fma_f32 v[62:63], v[62:63], v[2:3], v[138:139] op_sel_hi:[1,0,1] neg_lo:[0,0,1] neg_hi:[0,0,1]
	s_nop 0
	v_pk_fma_f32 v[134:135], v[62:63], v[62:63], v[134:135]
	v_mul_f32_e32 v138, v63, v63
	v_pk_add_f32 v[134:135], v[134:135], v[138:139] op_sel_hi:[1,0]
	ds_read2st64_b32 v[138:139], v3 offset0:78 offset1:79
	ds_read2st64_b32 v[140:141], v3 offset0:76 offset1:77
	ds_read2st64_b32 v[142:143], v3 offset0:74 offset1:75
	ds_read2st64_b32 v[144:145], v3 offset0:72 offset1:73
	s_waitcnt lgkmcnt(3)
	v_pk_fma_f32 v[54:55], v[54:55], v[2:3], v[138:139] op_sel_hi:[1,0,1] neg_lo:[0,0,1] neg_hi:[0,0,1]
	s_waitcnt lgkmcnt(2)
	v_pk_fma_f32 v[52:53], v[52:53], v[2:3], v[140:141] op_sel_hi:[1,0,1] neg_lo:[0,0,1] neg_hi:[0,0,1]
	s_waitcnt lgkmcnt(1)
	v_pk_fma_f32 v[58:59], v[58:59], v[116:117], v[142:143] op_sel_hi:[1,0,1] neg_lo:[0,0,1] neg_hi:[0,0,1]
	s_waitcnt lgkmcnt(0)
	v_pk_fma_f32 v[56:57], v[56:57], v[116:117], v[144:145] op_sel_hi:[1,0,1] neg_lo:[0,0,1] neg_hi:[0,0,1]
	v_pk_fma_f32 v[134:135], v[52:53], v[52:53], v[134:135]
	v_pk_fma_f32 v[136:137], v[56:57], v[56:57], v[136:137]
	v_mul_f32_e32 v144, v57, v57
	v_mul_f32_e32 v140, v53, v53
	v_pk_add_f32 v[136:137], v[144:145], v[136:137] op_sel_hi:[0,1]
	v_pk_add_f32 v[134:135], v[140:141], v[134:135] op_sel_hi:[0,1]
	v_pk_fma_f32 v[136:137], v[58:59], v[58:59], v[136:137]
	v_mul_f32_e32 v142, v59, v59
	v_pk_fma_f32 v[134:135], v[54:55], v[54:55], v[134:135]
	v_mul_f32_e32 v138, v55, v55
	v_pk_add_f32 v[136:137], v[142:143], v[136:137] op_sel_hi:[0,1]
	v_pk_add_f32 v[134:135], v[138:139], v[134:135] op_sel_hi:[0,1]
	ds_read2st64_b32 v[138:139], v3 offset0:86 offset1:87
	ds_read2st64_b32 v[140:141], v3 offset0:84 offset1:85
	ds_read2st64_b32 v[142:143], v3 offset0:82 offset1:83
	ds_read2st64_b32 v[144:145], v3 offset0:80 offset1:81
	s_waitcnt lgkmcnt(3)
	v_pk_fma_f32 v[46:47], v[46:47], v[2:3], v[138:139] op_sel_hi:[1,0,1] neg_lo:[0,0,1] neg_hi:[0,0,1]
	s_waitcnt lgkmcnt(2)
	v_pk_fma_f32 v[44:45], v[44:45], v[2:3], v[140:141] op_sel_hi:[1,0,1] neg_lo:[0,0,1] neg_hi:[0,0,1]
	s_waitcnt lgkmcnt(1)
	v_pk_fma_f32 v[50:51], v[50:51], v[116:117], v[142:143] op_sel_hi:[1,0,1] neg_lo:[0,0,1] neg_hi:[0,0,1]
	s_waitcnt lgkmcnt(0)
	v_pk_fma_f32 v[48:49], v[48:49], v[116:117], v[144:145] op_sel_hi:[1,0,1] neg_lo:[0,0,1] neg_hi:[0,0,1]
	v_pk_fma_f32 v[134:135], v[44:45], v[44:45], v[134:135]
	v_pk_fma_f32 v[136:137], v[48:49], v[48:49], v[136:137]
	v_mul_f32_e32 v144, v49, v49
	v_mul_f32_e32 v140, v45, v45
	v_pk_add_f32 v[136:137], v[144:145], v[136:137] op_sel_hi:[0,1]
	v_pk_add_f32 v[134:135], v[140:141], v[134:135] op_sel_hi:[0,1]
	v_pk_fma_f32 v[136:137], v[50:51], v[50:51], v[136:137]
	v_mul_f32_e32 v142, v51, v51
	v_pk_fma_f32 v[134:135], v[46:47], v[46:47], v[134:135]
	v_mul_f32_e32 v138, v47, v47
	v_pk_add_f32 v[136:137], v[142:143], v[136:137] op_sel_hi:[0,1]
	v_pk_add_f32 v[134:135], v[138:139], v[134:135] op_sel_hi:[0,1]
	ds_read2st64_b32 v[138:139], v3 offset0:94 offset1:95
	ds_read2st64_b32 v[140:141], v3 offset0:92 offset1:93
	ds_read2st64_b32 v[142:143], v3 offset0:90 offset1:91
	ds_read2st64_b32 v[144:145], v3 offset0:88 offset1:89
	s_waitcnt lgkmcnt(3)
	v_pk_fma_f32 v[38:39], v[38:39], v[2:3], v[138:139] op_sel_hi:[1,0,1] neg_lo:[0,0,1] neg_hi:[0,0,1]
	s_waitcnt lgkmcnt(2)
	v_pk_fma_f32 v[36:37], v[36:37], v[2:3], v[140:141] op_sel_hi:[1,0,1] neg_lo:[0,0,1] neg_hi:[0,0,1]
	v_mul_f32_e32 v138, v39, v39
	v_pk_fma_f32 v[134:135], v[36:37], v[36:37], v[134:135]
	v_mul_f32_e32 v140, v37, v37
	v_pk_add_f32 v[134:135], v[140:141], v[134:135] op_sel_hi:[0,1]
	v_pk_fma_f32 v[134:135], v[38:39], v[38:39], v[134:135]
	s_waitcnt lgkmcnt(0)
	v_pk_fma_f32 v[40:41], v[40:41], v[116:117], v[144:145] op_sel_hi:[1,0,1] neg_lo:[0,0,1] neg_hi:[0,0,1]
	v_pk_add_f32 v[134:135], v[138:139], v[134:135] op_sel_hi:[0,1]
	ds_read2st64_b32 v[138:139], v3 offset0:96 offset1:97
	v_pk_fma_f32 v[136:137], v[40:41], v[40:41], v[136:137]
	v_mul_f32_e32 v144, v41, v41
	v_pk_add_f32 v[136:137], v[144:145], v[136:137] op_sel_hi:[0,1]
	v_pk_fma_f32 v[42:43], v[42:43], v[116:117], v[142:143] op_sel_hi:[1,0,1] neg_lo:[0,0,1] neg_hi:[0,0,1]
	s_waitcnt lgkmcnt(0)
	v_pk_fma_f32 v[32:33], v[32:33], v[116:117], v[138:139] op_sel_hi:[1,0,1] neg_lo:[0,0,1] neg_hi:[0,0,1]
	v_pk_fma_f32 v[136:137], v[42:43], v[42:43], v[136:137]
	v_mul_f32_e32 v142, v43, v43
	v_pk_add_f32 v[136:137], v[142:143], v[136:137] op_sel_hi:[0,1]
	v_pk_fma_f32 v[136:137], v[32:33], v[32:33], v[136:137]
	v_mul_f32_e32 v138, v33, v33
	v_pk_add_f32 v[136:137], v[138:139], v[136:137] op_sel_hi:[0,1]
	ds_read2st64_b32 v[138:139], v3 offset0:98 offset1:99
	s_waitcnt lgkmcnt(0)
	v_pk_fma_f32 v[34:35], v[34:35], v[116:117], v[138:139] op_sel_hi:[1,0,1] neg_lo:[0,0,1] neg_hi:[0,0,1]
	s_nop 0
	v_pk_fma_f32 v[136:137], v[34:35], v[34:35], v[136:137]
	v_mul_f32_e32 v138, v35, v35
	v_pk_add_f32 v[136:137], v[138:139], v[136:137] op_sel_hi:[0,1]
	ds_read2st64_b32 v[138:139], v3 offset0:100 offset1:101
	s_waitcnt lgkmcnt(0)
	v_pk_fma_f32 v[28:29], v[28:29], v[2:3], v[138:139] op_sel_hi:[1,0,1] neg_lo:[0,0,1] neg_hi:[0,0,1]
	s_nop 0
	v_pk_fma_f32 v[134:135], v[28:29], v[28:29], v[134:135]
	v_mul_f32_e32 v138, v29, v29
	v_pk_add_f32 v[134:135], v[134:135], v[138:139] op_sel_hi:[1,0]
	ds_read2st64_b32 v[138:139], v3 offset0:102 offset1:103
	s_waitcnt lgkmcnt(0)
	v_pk_fma_f32 v[30:31], v[30:31], v[2:3], v[138:139] op_sel_hi:[1,0,1] neg_lo:[0,0,1] neg_hi:[0,0,1]
	s_nop 0
	v_pk_fma_f32 v[134:135], v[30:31], v[30:31], v[134:135]
	v_mul_f32_e32 v138, v31, v31
	v_pk_add_f32 v[134:135], v[134:135], v[138:139] op_sel_hi:[1,0]
	ds_read2st64_b32 v[138:139], v3 offset0:110 offset1:111
	ds_read2st64_b32 v[140:141], v3 offset0:108 offset1:109
	ds_read2st64_b32 v[142:143], v3 offset0:106 offset1:107
	ds_read2st64_b32 v[144:145], v3 offset0:104 offset1:105
	s_waitcnt lgkmcnt(3)
	v_pk_fma_f32 v[22:23], v[22:23], v[2:3], v[138:139] op_sel_hi:[1,0,1] neg_lo:[0,0,1] neg_hi:[0,0,1]
	s_waitcnt lgkmcnt(2)
	v_pk_fma_f32 v[20:21], v[20:21], v[2:3], v[140:141] op_sel_hi:[1,0,1] neg_lo:[0,0,1] neg_hi:[0,0,1]
	s_waitcnt lgkmcnt(1)
	v_pk_fma_f32 v[26:27], v[26:27], v[116:117], v[142:143] op_sel_hi:[1,0,1] neg_lo:[0,0,1] neg_hi:[0,0,1]
	s_waitcnt lgkmcnt(0)
	v_pk_fma_f32 v[24:25], v[24:25], v[116:117], v[144:145] op_sel_hi:[1,0,1] neg_lo:[0,0,1] neg_hi:[0,0,1]
	v_pk_fma_f32 v[134:135], v[20:21], v[20:21], v[134:135]
	v_pk_fma_f32 v[136:137], v[24:25], v[24:25], v[136:137]
	v_mul_f32_e32 v144, v25, v25
	v_mul_f32_e32 v140, v21, v21
	v_pk_add_f32 v[136:137], v[144:145], v[136:137] op_sel_hi:[0,1]
	v_pk_add_f32 v[134:135], v[140:141], v[134:135] op_sel_hi:[0,1]
	v_pk_fma_f32 v[136:137], v[26:27], v[26:27], v[136:137]
	v_mul_f32_e32 v142, v27, v27
	v_pk_fma_f32 v[134:135], v[22:23], v[22:23], v[134:135]
	v_mul_f32_e32 v138, v23, v23
	v_pk_add_f32 v[136:137], v[142:143], v[136:137] op_sel_hi:[0,1]
	v_pk_add_f32 v[134:135], v[138:139], v[134:135] op_sel_hi:[0,1]
	ds_read2st64_b32 v[138:139], v3 offset0:118 offset1:119
	ds_read2st64_b32 v[140:141], v3 offset0:116 offset1:117
	ds_read2st64_b32 v[142:143], v3 offset0:114 offset1:115
	ds_read2st64_b32 v[144:145], v3 offset0:112 offset1:113
	s_waitcnt lgkmcnt(3)
	v_pk_fma_f32 v[14:15], v[14:15], v[2:3], v[138:139] op_sel_hi:[1,0,1] neg_lo:[0,0,1] neg_hi:[0,0,1]
	s_waitcnt lgkmcnt(2)
	v_pk_fma_f32 v[12:13], v[12:13], v[2:3], v[140:141] op_sel_hi:[1,0,1] neg_lo:[0,0,1] neg_hi:[0,0,1]
	s_waitcnt lgkmcnt(1)
	v_pk_fma_f32 v[18:19], v[18:19], v[116:117], v[142:143] op_sel_hi:[1,0,1] neg_lo:[0,0,1] neg_hi:[0,0,1]
	s_waitcnt lgkmcnt(0)
	v_pk_fma_f32 v[16:17], v[16:17], v[116:117], v[144:145] op_sel_hi:[1,0,1] neg_lo:[0,0,1] neg_hi:[0,0,1]
	v_pk_fma_f32 v[134:135], v[12:13], v[12:13], v[134:135]
	v_pk_fma_f32 v[136:137], v[16:17], v[16:17], v[136:137]
	v_mul_f32_e32 v144, v17, v17
	v_mul_f32_e32 v140, v13, v13
	v_pk_add_f32 v[136:137], v[144:145], v[136:137] op_sel_hi:[0,1]
	v_pk_add_f32 v[134:135], v[140:141], v[134:135] op_sel_hi:[0,1]
	v_pk_fma_f32 v[136:137], v[18:19], v[18:19], v[136:137]
	v_mul_f32_e32 v142, v19, v19
	v_pk_fma_f32 v[134:135], v[14:15], v[14:15], v[134:135]
	v_mul_f32_e32 v138, v15, v15
	v_pk_add_f32 v[136:137], v[142:143], v[136:137] op_sel_hi:[0,1]
	v_pk_add_f32 v[138:139], v[138:139], v[134:135] op_sel_hi:[0,1]
	ds_read2st64_b32 v[140:141], v3 offset0:126 offset1:127
	ds_read2st64_b32 v[142:143], v3 offset0:124 offset1:125
	ds_read2st64_b32 v[144:145], v3 offset0:122 offset1:123
	ds_read2st64_b32 v[134:135], v3 offset0:120 offset1:121
	s_waitcnt lgkmcnt(3)
	v_pk_fma_f32 v[6:7], v[2:3], v[6:7], v[140:141] op_sel_hi:[0,1,1] neg_lo:[0,0,1] neg_hi:[0,0,1]
	s_waitcnt lgkmcnt(1)
	v_pk_fma_f32 v[10:11], v[10:11], v[116:117], v[144:145] op_sel_hi:[1,0,1] neg_lo:[0,0,1] neg_hi:[0,0,1]
	s_waitcnt lgkmcnt(0)
	v_pk_fma_f32 v[134:135], v[8:9], v[116:117], v[134:135] op_sel_hi:[1,0,1] neg_lo:[0,0,1] neg_hi:[0,0,1]
	v_mul_f32_e32 v116, v11, v11
	v_pk_fma_f32 v[8:9], v[134:135], v[134:135], v[136:137]
	v_mul_f32_e32 v136, v135, v135
	v_pk_add_f32 v[8:9], v[136:137], v[8:9] op_sel_hi:[0,1]
	v_pk_fma_f32 v[8:9], v[10:11], v[10:11], v[8:9]
	s_nop 0
	v_pk_add_f32 v[116:117], v[116:117], v[8:9] op_sel_hi:[0,1]
	v_pk_fma_f32 v[8:9], v[2:3], v[4:5], v[142:143] op_sel_hi:[0,1,1] neg_lo:[0,0,1] neg_hi:[0,0,1]
	v_pk_fma_f32 v[4:5], v[8:9], v[8:9], v[138:139]
	v_mul_f32_e32 v136, v9, v9
	v_pk_add_f32 v[4:5], v[136:137], v[4:5] op_sel_hi:[0,1]
	v_pk_fma_f32 v[2:3], v[6:7], v[6:7], v[4:5]
	v_mul_f32_e32 v4, v7, v7
	v_pk_add_f32 v[2:3], v[4:5], v[2:3] op_sel_hi:[0,1]
	v_mov_b32_e32 v3, v116
	s_nop 1
	v_permlane16_swap_b32_e32 v116, v3
	v_add_f32_e32 v3, v116, v3
	v_mov_b32_e32 v4, v3
	s_nop 1
	v_permlane32_swap_b32_e32 v3, v4
	v_add_f32_e32 v3, v3, v4
	v_fmamk_f32 v3, v3, 0x3b800000, v249
	v_rsq_f32_e32 v3, v3
	s_nop 0
	v_mul_f32_e32 v136, v193, v3
	v_mov_b32_e32 v3, v2
	s_nop 1
	v_permlane16_swap_b32_e32 v2, v3
	v_add_f32_e32 v2, v2, v3
	v_mov_b32_e32 v3, v2
	s_nop 1
	v_permlane32_swap_b32_e32 v2, v3
	v_add_f32_e32 v2, v2, v3
	v_fmamk_f32 v2, v2, 0x3b800000, v249
	v_rsq_f32_e32 v2, v2
	v_pk_mul_f32 v[102:103], v[102:103], v[136:137] op_sel_hi:[1,0]
	v_pk_mul_f32 v[100:101], v[100:101], v[136:137] op_sel_hi:[1,0]
	v_pk_mul_f32 v[10:11], v[10:11], v[136:137] op_sel_hi:[1,0]
	v_mul_f32_e32 v116, v193, v2
	v_ashrrev_i32_e32 v2, 2, v1
	v_and_b32_e32 v2, -4, v2
	v_ashrrev_i32_e32 v3, 31, v2
	v_lshl_add_u64 v[138:139], v[2:3], 2, s[4:5]
	v_lshl_add_u64 v[140:141], v[2:3], 1, s[42:43]
	global_load_dwordx4 v[2:5], v[138:139], off
	global_load_dwordx4 v[172:175], v[138:139], off offset:64
	global_load_dwordx4 v[176:179], v[138:139], off offset:128
	global_load_dwordx4 v[180:183], v[138:139], off offset:192
	global_load_dwordx4 v[184:187], v[138:139], off offset:256
	global_load_dwordx4 v[188:191], v[138:139], off offset:320
	global_load_dwordx4 v[230:233], v[138:139], off offset:384
	global_load_dwordx4 v[234:237], v[138:139], off offset:448
	global_load_dwordx4 v[238:241], v[138:139], off offset:512
	v_and_or_b32 v1, v1, 15, s52
	v_or_b32_e32 v142, s74, v1
	v_ashrrev_i32_e32 v143, 31, v142
	v_pk_mul_f32 v[6:7], v[6:7], v[116:117] op_sel_hi:[1,0]
	s_waitcnt vmcnt(8)
	v_pk_mul_f32 v[102:103], v[4:5], v[102:103]
	s_nop 0
	v_cvt_pk_bf16_f32 v145, v102, v103
	v_pk_mul_f32 v[102:103], v[104:105], v[116:117] op_sel_hi:[1,0]
	v_pk_mul_f32 v[100:101], v[2:3], v[100:101]
	v_pk_mul_f32 v[2:3], v[2:3], v[102:103]
	v_cvt_pk_bf16_f32 v144, v100, v101
	v_lshlrev_b64 v[100:101], 12, v[142:143]
	v_cvt_pk_bf16_f32 v102, v2, v3
	v_or_b32_e32 v2, 16, v142
	v_ashrrev_i32_e32 v3, 31, v2
	v_lshlrev_b64 v[2:3], 12, v[2:3]
	v_lshl_add_u64 v[100:101], v[140:141], 0, v[100:101]
	v_pk_mul_f32 v[104:105], v[106:107], v[116:117] op_sel_hi:[1,0]
	v_lshl_add_u64 v[2:3], v[140:141], 0, v[2:3]
	global_store_dwordx2 v[100:101], v[144:145], off
	v_pk_mul_f32 v[4:5], v[4:5], v[104:105]
	v_pk_mul_f32 v[106:107], v[114:115], v[136:137] op_sel_hi:[1,0]
	v_cvt_pk_bf16_f32 v103, v4, v5
	global_store_dwordx2 v[2:3], v[102:103], off
	v_pk_mul_f32 v[4:5], v[108:109], v[136:137] op_sel_hi:[1,0]
	s_waitcnt vmcnt(9)
	v_pk_mul_f32 v[106:107], v[174:175], v[106:107]
	v_pk_mul_f32 v[4:5], v[172:173], v[4:5]
	s_nop 0
	v_cvt_pk_bf16_f32 v4, v4, v5
	v_cvt_pk_bf16_f32 v5, v106, v107
	global_store_dwordx2 v[100:101], v[4:5], off offset:32
	v_pk_mul_f32 v[4:5], v[110:111], v[116:117] op_sel_hi:[1,0]
	v_pk_mul_f32 v[106:107], v[112:113], v[116:117] op_sel_hi:[1,0]
	v_pk_mul_f32 v[4:5], v[172:173], v[4:5]
	v_pk_mul_f32 v[174:175], v[174:175], v[106:107]
	v_cvt_pk_bf16_f32 v4, v4, v5
	v_pk_mul_f32 v[106:107], v[124:125], v[136:137] op_sel_hi:[1,0]
	v_cvt_pk_bf16_f32 v5, v174, v175
	global_store_dwordx2 v[2:3], v[4:5], off offset:32
	global_load_dwordx4 v[172:175], v[138:139], off offset:576
	v_pk_mul_f32 v[4:5], v[118:119], v[136:137] op_sel_hi:[1,0]
	s_waitcnt vmcnt(11)
	v_pk_mul_f32 v[106:107], v[106:107], v[178:179]
	v_pk_mul_f32 v[4:5], v[4:5], v[176:177]
	s_nop 0
	v_cvt_pk_bf16_f32 v4, v4, v5
	v_cvt_pk_bf16_f32 v5, v106, v107
	global_store_dwordx2 v[100:101], v[4:5], off offset:64
	v_pk_mul_f32 v[4:5], v[120:121], v[116:117] op_sel_hi:[1,0]
	v_pk_mul_f32 v[106:107], v[122:123], v[116:117] op_sel_hi:[1,0]
	v_pk_mul_f32 v[4:5], v[4:5], v[176:177]
	v_pk_mul_f32 v[178:179], v[106:107], v[178:179]
	v_cvt_pk_bf16_f32 v4, v4, v5
	v_pk_mul_f32 v[106:107], v[130:131], v[136:137] op_sel_hi:[1,0]
	v_cvt_pk_bf16_f32 v5, v178, v179
	global_store_dwordx2 v[2:3], v[4:5], off offset:64
	global_load_dwordx4 v[176:179], v[138:139], off offset:640
	v_pk_mul_f32 v[4:5], v[126:127], v[136:137] op_sel_hi:[1,0]
	s_waitcnt vmcnt(13)
	v_pk_mul_f32 v[106:107], v[106:107], v[182:183]
	v_pk_mul_f32 v[4:5], v[4:5], v[180:181]
	s_nop 0
	v_cvt_pk_bf16_f32 v4, v4, v5
	v_cvt_pk_bf16_f32 v5, v106, v107
	global_store_dwordx2 v[100:101], v[4:5], off offset:96
	v_pk_mul_f32 v[4:5], v[128:129], v[116:117] op_sel_hi:[1,0]
	v_pk_mul_f32 v[106:107], v[132:133], v[116:117] op_sel_hi:[1,0]
	v_pk_mul_f32 v[4:5], v[4:5], v[180:181]
	v_pk_mul_f32 v[182:183], v[106:107], v[182:183]
	v_cvt_pk_bf16_f32 v4, v4, v5
	s_nop 0
	v_cvt_pk_bf16_f32 v5, v182, v183
	global_store_dwordx2 v[2:3], v[4:5], off offset:96
	global_load_dwordx4 v[180:183], v[138:139], off offset:704
	v_pk_mul_f32 v[4:5], v[96:97], v[136:137] op_sel_hi:[1,0]
	v_pk_mul_f32 v[96:97], v[98:99], v[136:137] op_sel_hi:[1,0]
	s_waitcnt vmcnt(15)
	v_pk_mul_f32 v[4:5], v[4:5], v[184:185]
	v_pk_mul_f32 v[96:97], v[96:97], v[186:187]
	v_cvt_pk_bf16_f32 v4, v4, v5
	s_nop 0
	v_cvt_pk_bf16_f32 v5, v96, v97
	global_store_dwordx2 v[100:101], v[4:5], off offset:128
	v_pk_mul_f32 v[4:5], v[92:93], v[116:117] op_sel_hi:[1,0]
	v_pk_mul_f32 v[92:93], v[94:95], v[116:117] op_sel_hi:[1,0]
	v_pk_mul_f32 v[4:5], v[4:5], v[184:185]
	v_pk_mul_f32 v[92:93], v[92:93], v[186:187]
	v_cvt_pk_bf16_f32 v4, v4, v5
	s_nop 0
	v_cvt_pk_bf16_f32 v5, v92, v93
	global_store_dwordx2 v[2:3], v[4:5], off offset:128
	global_load_dwordx4 v[184:187], v[138:139], off offset:768
	v_pk_mul_f32 v[4:5], v[88:89], v[136:137] op_sel_hi:[1,0]
	v_pk_mul_f32 v[88:89], v[90:91], v[136:137] op_sel_hi:[1,0]
	s_waitcnt vmcnt(17)
	v_pk_mul_f32 v[4:5], v[4:5], v[188:189]
	v_pk_mul_f32 v[88:89], v[88:89], v[190:191]
	v_cvt_pk_bf16_f32 v4, v4, v5
	s_nop 0
	v_cvt_pk_bf16_f32 v5, v88, v89
	global_store_dwordx2 v[100:101], v[4:5], off offset:160
	v_pk_mul_f32 v[4:5], v[84:85], v[116:117] op_sel_hi:[1,0]
	v_pk_mul_f32 v[84:85], v[86:87], v[116:117] op_sel_hi:[1,0]
	v_pk_mul_f32 v[4:5], v[4:5], v[188:189]
	v_pk_mul_f32 v[84:85], v[84:85], v[190:191]
	v_cvt_pk_bf16_f32 v4, v4, v5
	s_nop 0
	v_cvt_pk_bf16_f32 v5, v84, v85
	global_store_dwordx2 v[2:3], v[4:5], off offset:160
	global_load_dwordx4 v[188:191], v[138:139], off offset:832
	v_pk_mul_f32 v[4:5], v[80:81], v[136:137] op_sel_hi:[1,0]
	v_pk_mul_f32 v[80:81], v[82:83], v[136:137] op_sel_hi:[1,0]
	s_waitcnt vmcnt(19)
	v_pk_mul_f32 v[4:5], v[4:5], v[230:231]
	v_pk_mul_f32 v[80:81], v[80:81], v[232:233]
	v_cvt_pk_bf16_f32 v4, v4, v5
	s_nop 0
	v_cvt_pk_bf16_f32 v5, v80, v81
	global_store_dwordx2 v[100:101], v[4:5], off offset:192
	v_pk_mul_f32 v[4:5], v[76:77], v[116:117] op_sel_hi:[1,0]
	v_pk_mul_f32 v[76:77], v[78:79], v[116:117] op_sel_hi:[1,0]
	v_pk_mul_f32 v[4:5], v[4:5], v[230:231]
	v_pk_mul_f32 v[76:77], v[76:77], v[232:233]
	v_cvt_pk_bf16_f32 v4, v4, v5
	s_nop 0
	v_cvt_pk_bf16_f32 v5, v76, v77
	global_store_dwordx2 v[2:3], v[4:5], off offset:192
	global_load_dwordx4 v[230:233], v[138:139], off offset:896
	v_pk_mul_f32 v[4:5], v[72:73], v[136:137] op_sel_hi:[1,0]
	v_pk_mul_f32 v[72:73], v[74:75], v[136:137] op_sel_hi:[1,0]
	s_waitcnt vmcnt(21)
	v_pk_mul_f32 v[4:5], v[4:5], v[234:235]
	v_pk_mul_f32 v[72:73], v[72:73], v[236:237]
	v_cvt_pk_bf16_f32 v4, v4, v5
	s_nop 0
	v_cvt_pk_bf16_f32 v5, v72, v73
	global_store_dwordx2 v[100:101], v[4:5], off offset:224
	v_pk_mul_f32 v[4:5], v[68:69], v[116:117] op_sel_hi:[1,0]
	v_pk_mul_f32 v[68:69], v[70:71], v[116:117] op_sel_hi:[1,0]
	v_pk_mul_f32 v[4:5], v[4:5], v[234:235]
	v_pk_mul_f32 v[68:69], v[68:69], v[236:237]
	v_cvt_pk_bf16_f32 v4, v4, v5
	s_nop 0
	v_cvt_pk_bf16_f32 v5, v68, v69
	global_store_dwordx2 v[2:3], v[4:5], off offset:224
	global_load_dwordx4 v[234:237], v[138:139], off offset:960
	v_pk_mul_f32 v[4:5], v[64:65], v[136:137] op_sel_hi:[1,0]
	v_pk_mul_f32 v[64:65], v[66:67], v[136:137] op_sel_hi:[1,0]
	s_waitcnt vmcnt(23)
	v_pk_mul_f32 v[4:5], v[4:5], v[238:239]
	v_pk_mul_f32 v[64:65], v[64:65], v[240:241]
	v_cvt_pk_bf16_f32 v4, v4, v5
	s_nop 0
	v_cvt_pk_bf16_f32 v5, v64, v65
	global_store_dwordx2 v[100:101], v[4:5], off offset:256
	v_pk_mul_f32 v[4:5], v[60:61], v[116:117] op_sel_hi:[1,0]
	v_pk_mul_f32 v[60:61], v[62:63], v[116:117] op_sel_hi:[1,0]
	v_pk_mul_f32 v[4:5], v[4:5], v[238:239]
	v_pk_mul_f32 v[60:61], v[60:61], v[240:241]
	v_cvt_pk_bf16_f32 v4, v4, v5
	s_nop 0
	v_cvt_pk_bf16_f32 v5, v60, v61
	global_store_dwordx2 v[2:3], v[4:5], off offset:256
	v_pk_mul_f32 v[4:5], v[56:57], v[136:137] op_sel_hi:[1,0]
	v_pk_mul_f32 v[56:57], v[58:59], v[136:137] op_sel_hi:[1,0]
	s_waitcnt vmcnt(20)
	v_pk_mul_f32 v[4:5], v[4:5], v[172:173]
	v_pk_mul_f32 v[56:57], v[56:57], v[174:175]
	v_cvt_pk_bf16_f32 v4, v4, v5
	s_nop 0
	v_cvt_pk_bf16_f32 v5, v56, v57
	global_store_dwordx2 v[100:101], v[4:5], off offset:288
	v_pk_mul_f32 v[4:5], v[52:53], v[116:117] op_sel_hi:[1,0]
	v_pk_mul_f32 v[52:53], v[54:55], v[116:117] op_sel_hi:[1,0]
	v_pk_mul_f32 v[4:5], v[4:5], v[172:173]
	v_pk_mul_f32 v[52:53], v[52:53], v[174:175]
	v_cvt_pk_bf16_f32 v4, v4, v5
	s_nop 0
	v_cvt_pk_bf16_f32 v5, v52, v53
	global_store_dwordx2 v[2:3], v[4:5], off offset:288
	v_pk_mul_f32 v[4:5], v[48:49], v[136:137] op_sel_hi:[1,0]
	v_pk_mul_f32 v[48:49], v[50:51], v[136:137] op_sel_hi:[1,0]
	s_waitcnt vmcnt(19)
	v_pk_mul_f32 v[4:5], v[4:5], v[176:177]
	v_pk_mul_f32 v[48:49], v[48:49], v[178:179]
	v_cvt_pk_bf16_f32 v4, v4, v5
	s_nop 0
	v_cvt_pk_bf16_f32 v5, v48, v49
	global_store_dwordx2 v[100:101], v[4:5], off offset:320
	v_pk_mul_f32 v[4:5], v[44:45], v[116:117] op_sel_hi:[1,0]
	v_pk_mul_f32 v[44:45], v[46:47], v[116:117] op_sel_hi:[1,0]
	v_pk_mul_f32 v[4:5], v[4:5], v[176:177]
	v_pk_mul_f32 v[44:45], v[44:45], v[178:179]
	v_cvt_pk_bf16_f32 v4, v4, v5
	s_nop 0
	v_cvt_pk_bf16_f32 v5, v44, v45
	global_store_dwordx2 v[2:3], v[4:5], off offset:320
	v_pk_mul_f32 v[4:5], v[40:41], v[136:137] op_sel_hi:[1,0]
	v_pk_mul_f32 v[40:41], v[42:43], v[136:137] op_sel_hi:[1,0]
	s_waitcnt vmcnt(18)
	v_pk_mul_f32 v[4:5], v[4:5], v[180:181]
	v_pk_mul_f32 v[40:41], v[40:41], v[182:183]
	v_cvt_pk_bf16_f32 v4, v4, v5
	s_nop 0
	v_cvt_pk_bf16_f32 v5, v40, v41
	global_store_dwordx2 v[100:101], v[4:5], off offset:352
	v_pk_mul_f32 v[4:5], v[36:37], v[116:117] op_sel_hi:[1,0]
	v_pk_mul_f32 v[36:37], v[38:39], v[116:117] op_sel_hi:[1,0]
	v_pk_mul_f32 v[4:5], v[4:5], v[180:181]
	v_pk_mul_f32 v[36:37], v[36:37], v[182:183]
	v_cvt_pk_bf16_f32 v4, v4, v5
	s_nop 0
	v_cvt_pk_bf16_f32 v5, v36, v37
	global_store_dwordx2 v[2:3], v[4:5], off offset:352
	v_pk_mul_f32 v[4:5], v[32:33], v[136:137] op_sel_hi:[1,0]
	v_pk_mul_f32 v[32:33], v[34:35], v[136:137] op_sel_hi:[1,0]
	s_waitcnt vmcnt(17)
	v_pk_mul_f32 v[4:5], v[4:5], v[184:185]
	v_pk_mul_f32 v[32:33], v[32:33], v[186:187]
	v_cvt_pk_bf16_f32 v4, v4, v5
	s_nop 0
	v_cvt_pk_bf16_f32 v5, v32, v33
	global_store_dwordx2 v[100:101], v[4:5], off offset:384
	v_pk_mul_f32 v[4:5], v[28:29], v[116:117] op_sel_hi:[1,0]
	v_pk_mul_f32 v[28:29], v[30:31], v[116:117] op_sel_hi:[1,0]
	v_pk_mul_f32 v[4:5], v[4:5], v[184:185]
	v_pk_mul_f32 v[28:29], v[28:29], v[186:187]
	v_cvt_pk_bf16_f32 v4, v4, v5
	s_nop 0
	v_cvt_pk_bf16_f32 v5, v28, v29
	global_store_dwordx2 v[2:3], v[4:5], off offset:384
	v_pk_mul_f32 v[4:5], v[24:25], v[136:137] op_sel_hi:[1,0]
	v_pk_mul_f32 v[24:25], v[26:27], v[136:137] op_sel_hi:[1,0]
	s_waitcnt vmcnt(16)
	v_pk_mul_f32 v[4:5], v[4:5], v[188:189]
	v_pk_mul_f32 v[24:25], v[24:25], v[190:191]
	v_cvt_pk_bf16_f32 v4, v4, v5
	s_nop 0
	v_cvt_pk_bf16_f32 v5, v24, v25
	global_store_dwordx2 v[100:101], v[4:5], off offset:416
	v_pk_mul_f32 v[4:5], v[20:21], v[116:117] op_sel_hi:[1,0]
	v_pk_mul_f32 v[20:21], v[22:23], v[116:117] op_sel_hi:[1,0]
	v_pk_mul_f32 v[4:5], v[4:5], v[188:189]
	v_pk_mul_f32 v[20:21], v[20:21], v[190:191]
	v_cvt_pk_bf16_f32 v4, v4, v5
	s_nop 0
	v_cvt_pk_bf16_f32 v5, v20, v21
	global_store_dwordx2 v[2:3], v[4:5], off offset:416
	v_pk_mul_f32 v[4:5], v[16:17], v[136:137] op_sel_hi:[1,0]
	v_pk_mul_f32 v[16:17], v[18:19], v[136:137] op_sel_hi:[1,0]
	s_waitcnt vmcnt(15)
	v_pk_mul_f32 v[4:5], v[4:5], v[230:231]
	v_pk_mul_f32 v[16:17], v[16:17], v[232:233]
	v_cvt_pk_bf16_f32 v4, v4, v5
	s_nop 0
	v_cvt_pk_bf16_f32 v5, v16, v17
	global_store_dwordx2 v[100:101], v[4:5], off offset:448
	v_pk_mul_f32 v[4:5], v[12:13], v[116:117] op_sel_hi:[1,0]
	v_pk_mul_f32 v[12:13], v[14:15], v[116:117] op_sel_hi:[1,0]
	v_pk_mul_f32 v[4:5], v[4:5], v[230:231]
	v_pk_mul_f32 v[12:13], v[12:13], v[232:233]
	v_cvt_pk_bf16_f32 v4, v4, v5
	s_nop 0
	v_cvt_pk_bf16_f32 v5, v12, v13
	global_store_dwordx2 v[2:3], v[4:5], off offset:448
	v_pk_mul_f32 v[4:5], v[134:135], v[136:137] op_sel_hi:[1,0]
	s_waitcnt vmcnt(14)
	v_pk_mul_f32 v[10:11], v[10:11], v[236:237]
	v_pk_mul_f32 v[4:5], v[4:5], v[234:235]
	v_pk_mul_f32 v[6:7], v[6:7], v[236:237]
	v_cvt_pk_bf16_f32 v4, v4, v5
	v_cvt_pk_bf16_f32 v5, v10, v11
	global_store_dwordx2 v[100:101], v[4:5], off offset:480
	v_pk_mul_f32 v[4:5], v[8:9], v[116:117] op_sel_hi:[1,0]
	s_nop 0
	v_pk_mul_f32 v[4:5], v[4:5], v[234:235]
	s_nop 0
	v_cvt_pk_bf16_f32 v4, v4, v5
	v_cvt_pk_bf16_f32 v5, v6, v7
	global_store_dwordx2 v[2:3], v[4:5], off offset:480
	s_branch .LBB0_686
